# as previous with scan-shadow conversion budget 5 iterations
# baseline (speedup 1.0000x reference)
; #define LAS __attribute__((address_space(3)))
; __device__ __forceinline__ void convert_layer_static(const PT& a, LAS unsigned char* lds, int l, int gw, int NGW, int wave, int lane, int r_end = IT_LAYER) {
;     for (int r = 2 * gw; r < r_end; r += 2 * NGW) cv_pair(a, lds, l, r, wave, lane);
; }
; __device__ __forceinline__ void prologue_a(const PT& a, LAS unsigned char* lds) {
;     ...
;     convert_layer_static(a, lds, 0, gw, NGW, wave, lane);
;     for (int cl_ = 1; cl_ < DEPTH; ++cl_) convert_layer_static(a, lds, cl_, gw, NGW, wave, lane, CV_PRO_ITEMS);
.LBB0_110:
	s_or_b64 exec, exec, s[12:13]
	v_lshl_add_u32 v2, v74, 2, v115
	v_add_u32_e32 v3, v115, v113
	s_mov_b32 s13, 0
	v_lshl_add_u32 v113, v67, 2, v3
	v_lshl_add_u32 v115, v69, 2, v3
	v_lshl_add_u32 v117, v97, 2, v3
	v_lshl_add_u32 v119, v99, 2, v3
	s_mov_b32 s18, 1
	s_lshl_b32 s42, s17, 5
	s_movk_i32 s43, 0x393f
	s_movk_i32 s44, 0x453f
	s_movk_i32 s45, 0x4d3f
	s_movk_i32 s46, 0x793f
	s_movk_i32 s47, 0x15ff
	s_movk_i32 s48, 0xba3
	s_movk_i32 s49, 0x1600
	s_movk_i32 s50, 0x3ff
	v_mov_b32_e32 v79, 0
	s_mov_b64 s[20:21], 0xea00000
	s_mov_b32 s51, 0x478bbced
	s_movk_i32 s52, 0x9f
	s_movk_i32 s53, 0x109
	v_add_u32_e32 v121, v2, v121
	v_lshlrev_b64 v[76:77], 1, v[76:77]
	s_mov_b32 s54, 0x473f
	v_readlane_b32 s100, v252, 4
	s_cmp_eq_u32 s100, 0x100
	s_cselect_b32 s54, s54, 0x8f3f
	v_mov_b32_e32 v123, 0xea00
	v_mov_b32_e32 v125, 5
	v_mov_b32_e32 v128, 0x23a40
	v_mov_b32_e32 v129, 0x23a38
	v_mov_b32_e32 v130, 6
	v_mov_b32_e32 v131, 0x80
	v_mov_b32_e32 v132, 0x23a20
	v_mov_b32_e32 v133, 0x23a18
	v_mov_b32_e32 v134, 0x23a10
	s_branch .LBB0_112

;     __device__ __forceinline__ const float* in(int i) const { return (const float*)(const GAS float*)raw(i); }
;     __device__ __forceinline__ unsigned char* ws() const { return (unsigned char*)(GAS unsigned char*)raw(N_INPUTS + 1); }
; __device__ __forceinline__ CvItem cv_decode(const PT& a, int l, int r) {
;     unsigned char* ws = a.ws(); CvItem it;
;     if (r < IT_WIN) { const int kb = r / 458, nb = r % 458, n0 = nb * 32;
;         int drow; if (n0 < 2048) drow = n0; else if (n0 < 5120) drow = NIN_MAIN + (n0 - 2048); else if (n0 < 8512) drow = 2048 + (n0 - 5120); else drow = 5632 + (n0 - 8512);
;         it = CvItem{a.in(I_W_IN) + (size_t)l * D * NIN, NIN, kb * 64, n0, (bf16_t*)(ws + WS_WIN + l * WIN_L), D, drow, a.in(I_NORM_MIX_G) + l * D}; return it; }
;     r -= IT_WIN;
;     if (r < 3 * IT_BR) { const int br = r / IT_BR; r -= br * IT_BR; const int kb = r / 64, nb = r % 64;
;         it = CvItem{a.in(br == 0 ? I_W_BR_A : (br == 1 ? I_W_BR_B : I_W_BR_C)) + (size_t)l * 1024 * D, D, kb * 64, nb * 32, (bf16_t*)(ws + WS_WBR + l * WBR_L) + (size_t)br * D * 1024, 1024, nb * 32, nullptr}; return it; }
;     r -= 3 * IT_BR;
;     if (r < IT_OUT) { const int kb = r / 64, nb = r % 64;
;         it = CvItem{a.in(I_W_OUT) + (size_t)l * D * D, D, kb * 64, nb * 32, (bf16_t*)(ws + WS_WOUT + l * WOUT_L), D, nb * 32, nullptr}; return it; }
;     r -= IT_OUT;
;     if (r < 2 * IT_GU) { const int up = r / IT_GU; r -= up * IT_GU; const int kb = r / 176, nb = r % 176, n0 = nb * 32;
;         it = CvItem{a.in(up ? I_W_FFN_UP : I_W_FFN_GATE) + (size_t)l * D * DFF, DFF, kb * 64, n0, (bf16_t*)(ws + WS_WGU + l * WGU_L), D, 256 * (n0 / 128) + (n0 % 128) + 128 * up, a.in(I_NORM_FFN_G) + l * D}; return it; }
;     r -= 2 * IT_GU;
;     { const int kb = r / 64, nb = r % 64;
;       it = CvItem{a.in(I_W_FFN_DOWN) + (size_t)l * DFF * D, D, kb * 64, nb * 32, (bf16_t*)(ws + WS_WDN + l * WDN_L), DFF, nb * 32, nullptr}; }
;     for (int it = 0; it < budget; ++it) {
;         unsigned r = 0; if (lane == 0) r = __hip_atomic_fetch_add(ctr, 2u, __ATOMIC_RELAXED, __HIP_MEMORY_SCOPE_AGENT);
;         r = (unsigned)__builtin_amdgcn_readfirstlane((int)r) + (unsigned)CV_PRO_ITEMS;
;         if (r >= (unsigned)IT_LAYER) break;
;         cv_pair(a, lds, l, (int)r, wave, lane);
.LcvqA_1381:
	s_mov_b32 s24, s100
	s_add_u32 s100, s100, 0xc00
	s_add_i32 s24, s24, 0xffffb800
	s_cmp_lt_u32 s24, 0xffff70c0
	s_mov_b64 s[2:3], -1
	s_cbranch_scc1 .LcvqA_1380
	v_mov_b32_e32 v2, 0x23a60
	s_add_i32 s15, s24, 0x8f40
	v_add_u32_e32 v2, 0, v2
	ds_read_b64 v[2:3], v2
	s_cmpk_gt_u32 s15, 0x393f
	s_waitcnt lgkmcnt(0)
	v_readfirstlane_b32 s20, v3
	v_readfirstlane_b32 s21, v2
	s_cbranch_scc0 .LcvqA_1399
	s_cmpk_gt_u32 s15, 0x453f
	s_cbranch_scc0 .LcvqA_1396
	s_cmpk_gt_u32 s15, 0x4d3f
	s_mov_b64 s[18:19], -1
	s_cbranch_scc0 .LcvqA_1393
	s_cmpk_gt_u32 s15, 0x793f
	s_cbranch_scc0 .LcvqA_1391
	v_mov_b32_e32 v2, 0x23a48
	s_and_b32 s2, s15, 0x7fffffc0
	v_add_u32_e32 v2, 0, v2
	ds_read_b64 v[2:3], v2
	s_add_i32 s14, s2, 0xffff86c0
	s_waitcnt lgkmcnt(0)
	v_readfirstlane_b32 s3, v2
	v_readfirstlane_b32 s2, v3
	s_add_u32 s30, s3, s34
	s_addc_u32 s31, s2, s33
	s_lshl_b32 s2, s15, 5
	s_and_b32 s25, s2, 0x7e0
	s_add_u32 s2, s21, s50
	s_addc_u32 s3, s20, s35
	s_add_u32 s12, s2, 0x1ea00000
	s_addc_u32 s13, s3, 0
	s_mov_b64 s[2:3], 0

; __device__ __forceinline__ int opaque_tid() { int t = threadIdx.x; asm volatile("" : "+v"(t)); return t; }
;     for (int it = 0; it < budget; ++it) {
;         unsigned r = 0; if (lane == 0) r = __hip_atomic_fetch_add(ctr, 2u, __ATOMIC_RELAXED, __HIP_MEMORY_SCOPE_AGENT);
;         r = (unsigned)__builtin_amdgcn_readfirstlane((int)r) + (unsigned)CV_PRO_ITEMS;
;         if (r >= (unsigned)IT_LAYER) break;
;         cv_pair(a, lds, l, (int)r, wave, lane);
;     }
; }
; __global__ void __launch_bounds__(NTHREADS, 2) mk_fwd(Args args) {
;     ...
;             if (l + 1 < DEPTH && !(G >= 256 && bid < 128)) { __syncthreads(); const int tid_ = opaque_tid(); convert_layer_queue(pt, lds, l + 1, cvq, tid_ >> 6, tid_ & 63); }
.LBB0_1377:
	s_cmp_eq_u32 s64, 3
	v_readlane_b32 s2, v253, 61
	s_cselect_b64 s[0:1], -1, 0
	v_readlane_b32 s3, v253, 62
	s_or_b64 s[0:1], s[2:3], s[0:1]
	v_readlane_b32 s2, v252, 4
	s_cmp_lg_u32 s2, 0x100
	s_cselect_b64 s[2:3], -1, 0
	s_or_b64 s[0:1], s[0:1], s[2:3]
	v_readlane_b32 s28, v254, 55
	s_mov_b32 s36, s64
	s_and_b64 vcc, exec, s[0:1]
	v_readlane_b32 s29, v254, 56
	s_cbranch_vccnz .LBB0_1470
	v_readlane_b32 s0, v254, 53
	v_readlane_b32 s1, v254, 54
	s_mov_b32 s3, s1
	s_lshl_b32 s2, s36, 6
	s_lshl_b64 s[0:1], s[2:3], 2
	v_readlane_b32 s4, v254, 60
	v_readlane_b32 s5, v254, 61
	s_add_u32 s0, s4, s0
	s_addc_u32 s1, s5, s1
	s_add_u32 s0, s0, 0x8000
	s_addc_u32 s1, s1, 0
	s_add_i32 s2, s36, 1
	s_mul_hi_u32 s33, s2, 0x2c00000
	s_mul_i32 s34, s2, 0x2c00000
	s_mul_hi_u32 s35, s2, 0x1600000
	s_mul_i32 s50, s2, 0x1600000
	s_lshl_b32 s6, s2, 11
	s_mov_b32 s7, s3
	s_lshl_b64 s[8:9], s[2:3], 24
	s_lshl_b64 s[10:11], s[2:3], 23
	s_mul_hi_u32 s51, s2, 0xc00000
	s_mul_i32 s52, s2, 0xc00000
	s_mul_hi_u32 s53, s2, 0x7280000
	s_mul_i32 s54, s2, 0x7280000
	s_mul_hi_u32 s55, s2, 0x3a00000
	v_writelane_b32 v254, s2, 53
	v_mov_b32_e32 v2, v0
	s_mul_i32 s56, s2, 0x3a00000
	v_writelane_b32 v254, s3, 54
	s_waitcnt vmcnt(0) lgkmcnt(0)
	s_barrier
	s_movk_i32 s2, 0x4200
	v_lshrrev_b32_e32 v1, 6, v2
	v_and_b32_e32 v3, 63, v2
	v_readfirstlane_b32 s100, v1
	v_readlane_b32 s101, v252, 0
	s_sub_u32 s101, s101, 128
	s_lshl_b32 s101, s101, 3
	s_add_u32 s100, s100, s101
	s_lshl_b32 s100, s100, 1
	s_add_u32 s100, s100, 0x1800
	v_mul_lo_u32 v1, v1, s2
	v_cmp_eq_u32_e64 s[40:41], 0, v3
	v_add_u32_e32 v3, 0, v1
	v_lshlrev_b32_e32 v1, 2, v2
	v_and_b32_e32 v66, 28, v1
	v_bfe_u32 v1, v2, 3, 3
	v_lshlrev_b32_e32 v2, 3, v2
	v_and_b32_e32 v68, 56, v2
	v_lshl_add_u32 v4, v66, 2, v3
	v_mul_u32_u24_e32 v5, 0x84, v1
	v_mul_u32_u24_e32 v2, 0x84, v68
	v_lshlrev_b32_e32 v6, 2, v1
	v_or_b32_e32 v67, 8, v1
	v_or_b32_e32 v69, 16, v1
	v_or_b32_e32 v71, 24, v1
	v_or_b32_e32 v73, 32, v1
	v_or_b32_e32 v75, 40, v1
	v_or_b32_e32 v77, 48, v1
	v_or_b32_e32 v79, 56, v1
	v_add3_u32 v81, v3, v2, v6
	s_mov_b32 s57, 0x5
	v_add_u32_e32 v83, v4, v5
	s_branch .LBB0_1381

;     __device__ __forceinline__ const float* in(int i) const { return (const float*)(const GAS float*)raw(i); }
;     __device__ __forceinline__ unsigned char* ws() const { return (unsigned char*)(GAS unsigned char*)raw(N_INPUTS + 1); }
; __device__ __forceinline__ CvItem cv_decode(const PT& a, int l, int r) {
;     unsigned char* ws = a.ws(); CvItem it;
;     if (r < IT_WIN) { const int kb = r / 458, nb = r % 458, n0 = nb * 32;
;         int drow; if (n0 < 2048) drow = n0; else if (n0 < 5120) drow = NIN_MAIN + (n0 - 2048); else if (n0 < 8512) drow = 2048 + (n0 - 5120); else drow = 5632 + (n0 - 8512);
;         it = CvItem{a.in(I_W_IN) + (size_t)l * D * NIN, NIN, kb * 64, n0, (bf16_t*)(ws + WS_WIN + l * WIN_L), D, drow, a.in(I_NORM_MIX_G) + l * D}; return it; }
;     r -= IT_WIN;
;     if (r < 3 * IT_BR) { const int br = r / IT_BR; r -= br * IT_BR; const int kb = r / 64, nb = r % 64;
;         it = CvItem{a.in(br == 0 ? I_W_BR_A : (br == 1 ? I_W_BR_B : I_W_BR_C)) + (size_t)l * 1024 * D, D, kb * 64, nb * 32, (bf16_t*)(ws + WS_WBR + l * WBR_L) + (size_t)br * D * 1024, 1024, nb * 32, nullptr}; return it; }
;     r -= 3 * IT_BR;
;     if (r < IT_OUT) { const int kb = r / 64, nb = r % 64;
;         it = CvItem{a.in(I_W_OUT) + (size_t)l * D * D, D, kb * 64, nb * 32, (bf16_t*)(ws + WS_WOUT + l * WOUT_L), D, nb * 32, nullptr}; return it; }
;     r -= IT_OUT;
;     if (r < 2 * IT_GU) { const int up = r / IT_GU; r -= up * IT_GU; const int kb = r / 176, nb = r % 176, n0 = nb * 32;
;         it = CvItem{a.in(up ? I_W_FFN_UP : I_W_FFN_GATE) + (size_t)l * D * DFF, DFF, kb * 64, n0, (bf16_t*)(ws + WS_WGU + l * WGU_L), D, 256 * (n0 / 128) + (n0 % 128) + 128 * up, a.in(I_NORM_FFN_G) + l * D}; return it; }
;     r -= 2 * IT_GU;
;     { const int kb = r / 64, nb = r % 64;
;       it = CvItem{a.in(I_W_FFN_DOWN) + (size_t)l * DFF * D, D, kb * 64, nb * 32, (bf16_t*)(ws + WS_WDN + l * WDN_L), DFF, nb * 32, nullptr}; }
;     for (int it = 0; it < budget; ++it) {
;         unsigned r = 0; if (lane == 0) r = __hip_atomic_fetch_add(ctr, 2u, __ATOMIC_RELAXED, __HIP_MEMORY_SCOPE_AGENT);
;         r = (unsigned)__builtin_amdgcn_readfirstlane((int)r) + (unsigned)CV_PRO_ITEMS;
;         if (r >= (unsigned)IT_LAYER) break;
;         cv_pair(a, lds, l, (int)r, wave, lane);
.LBB0_1381:
	s_mov_b32 s24, s100
	s_add_u32 s100, s100, 0x800
	s_add_i32 s24, s24, 0xffffb800
	s_cmp_lt_u32 s24, 0xffff70c0
	s_mov_b64 s[2:3], -1
	s_cbranch_scc1 .LBB0_1380
	v_mov_b32_e32 v2, 0x23a60
	s_add_i32 s15, s24, 0x8f40
	v_add_u32_e32 v2, 0, v2
	ds_read_b64 v[2:3], v2
	s_cmpk_gt_u32 s15, 0x393f
	s_waitcnt lgkmcnt(0)
	v_readfirstlane_b32 s20, v3
	v_readfirstlane_b32 s21, v2
	s_cbranch_scc0 .LBB0_1399
	s_cmpk_gt_u32 s15, 0x453f
	s_cbranch_scc0 .LBB0_1396
	s_cmpk_gt_u32 s15, 0x4d3f
	s_mov_b64 s[18:19], -1
	s_cbranch_scc0 .LBB0_1393
	s_cmpk_gt_u32 s15, 0x793f
	s_cbranch_scc0 .LBB0_1391
	v_mov_b32_e32 v2, 0x23a48
	s_and_b32 s2, s15, 0x7fffffc0
	v_add_u32_e32 v2, 0, v2
	ds_read_b64 v[2:3], v2
	s_add_i32 s14, s2, 0xffff86c0
	s_waitcnt lgkmcnt(0)
	v_readfirstlane_b32 s3, v2
	v_readfirstlane_b32 s2, v3
	s_add_u32 s30, s3, s34
	s_addc_u32 s31, s2, s33
	s_lshl_b32 s2, s15, 5
	s_and_b32 s25, s2, 0x7e0
	s_add_u32 s2, s21, s50
	s_addc_u32 s3, s20, s35
	s_add_u32 s12, s2, 0x1ea00000
	s_addc_u32 s13, s3, 0
	s_mov_b64 s[2:3], 0

; __device__ __forceinline__ int opaque_tid() { int t = threadIdx.x; asm volatile("" : "+v"(t)); return t; }
;     for (int it = 0; it < budget; ++it) {
;         unsigned r = 0; if (lane == 0) r = __hip_atomic_fetch_add(ctr, 2u, __ATOMIC_RELAXED, __HIP_MEMORY_SCOPE_AGENT);
;         r = (unsigned)__builtin_amdgcn_readfirstlane((int)r) + (unsigned)CV_PRO_ITEMS;
;         if (r >= (unsigned)IT_LAYER) break;
;         cv_pair(a, lds, l, (int)r, wave, lane);
;     }
; }
; __global__ void __launch_bounds__(NTHREADS, 2) mk_fwd(Args args) {
;     ...
;             if (l + 1 < DEPTH && !(G >= 256 && bid < 128)) { __syncthreads(); const int tid_ = opaque_tid(); convert_layer_queue(pt, lds, l + 1, cvq, tid_ >> 6, tid_ & 63); }
.LBB0_1843:
	v_readlane_b32 s2, v252, 4
	s_cmp_lg_u32 s2, 0x100
	s_cbranch_scc1 .LcvqB_skip
	v_readlane_b32 s2, v252, 0
	s_cmp_lt_u32 s2, 128
	s_cbranch_scc1 .LcvqB_skip
	s_cmp_gt_u32 s36, 2
	s_cbranch_scc1 .LcvqB_skip
	v_writelane_b32 v255, s0, 8
	v_writelane_b32 v255, s1, 9
	v_writelane_b32 v255, s40, 10
	v_writelane_b32 v255, s41, 11
	s_mov_b32 s64, s36
	v_readlane_b32 s0, v254, 53
	v_readlane_b32 s1, v254, 54
	s_mov_b32 s3, s1
	s_lshl_b32 s2, s36, 6
	s_lshl_b64 s[0:1], s[2:3], 2
	v_readlane_b32 s4, v254, 60
	v_readlane_b32 s5, v254, 61
	s_add_u32 s0, s4, s0
	s_addc_u32 s1, s5, s1
	s_add_u32 s0, s0, 0x8000
	s_addc_u32 s1, s1, 0
	s_add_i32 s2, s36, 1
	s_mul_hi_u32 s33, s2, 0x2c00000
	s_mul_i32 s34, s2, 0x2c00000
	s_mul_hi_u32 s35, s2, 0x1600000
	s_mul_i32 s50, s2, 0x1600000
	s_lshl_b32 s6, s2, 11
	s_mov_b32 s7, s3
	s_lshl_b64 s[8:9], s[2:3], 24
	s_lshl_b64 s[10:11], s[2:3], 23
	s_mul_hi_u32 s51, s2, 0xc00000
	s_mul_i32 s52, s2, 0xc00000
	s_mul_hi_u32 s53, s2, 0x7280000
	s_mul_i32 s54, s2, 0x7280000
	s_mul_hi_u32 s55, s2, 0x3a00000
	v_writelane_b32 v254, s2, 53
	v_mov_b32_e32 v2, v0
	s_mul_i32 s56, s2, 0x3a00000
	v_writelane_b32 v254, s3, 54
	s_waitcnt vmcnt(0) lgkmcnt(0)
	s_barrier
	s_movk_i32 s2, 0x4200
	v_lshrrev_b32_e32 v1, 6, v2
	v_and_b32_e32 v3, 63, v2
	v_readfirstlane_b32 s100, v1
	v_readlane_b32 s101, v252, 0
	s_sub_u32 s101, s101, 128
	s_lshl_b32 s101, s101, 3
	s_add_u32 s100, s100, s101
	s_lshl_b32 s100, s100, 1
	s_add_u32 s100, s100, 0x4000
	v_mul_lo_u32 v1, v1, s2
	v_cmp_eq_u32_e64 s[40:41], 0, v3
	v_add_u32_e32 v3, 0, v1
	v_lshlrev_b32_e32 v1, 2, v2
	v_and_b32_e32 v66, 28, v1
	v_bfe_u32 v1, v2, 3, 3
	v_lshlrev_b32_e32 v2, 3, v2
	v_and_b32_e32 v68, 56, v2
	v_lshl_add_u32 v4, v66, 2, v3
	v_mul_u32_u24_e32 v5, 0x84, v1
	v_mul_u32_u24_e32 v2, 0x84, v68
	v_lshlrev_b32_e32 v6, 2, v1
	v_or_b32_e32 v67, 8, v1
	v_or_b32_e32 v69, 16, v1
	v_or_b32_e32 v71, 24, v1
	v_or_b32_e32 v73, 32, v1
	v_or_b32_e32 v75, 40, v1
	v_or_b32_e32 v77, 48, v1
	v_or_b32_e32 v79, 56, v1
	v_add3_u32 v81, v3, v2, v6
	s_mov_b32 s57, 0x1
	v_add_u32_e32 v83, v4, v5
	s_branch .LcvqB_1381
